# UP: SW bias-row loads requested at unit set-up into registers outside the K-loop; epilogue's first wait vmcnt(0)->vmcnt(8) so it no longer drains the next unit's prefetch DMAs; on top of v59
# baseline (speedup 1.0000x reference)
;     __host__ __device__ __forceinline__ bool next(int i, Unit& u) const { const int vv = vid + (i / 5) * G; if (vv >= 256) return false; u.pm = vv >> 2; u.pn = (vv & 3) + 4 * (i % 5); return true; }
;     __host__ __device__ __forceinline__ bool next(int i, pg8::Unit& u) const { const long Lx = (long)i * G + c; if (Lx >= 128) return false; const int Lq = (int)Lx; u.pm = 8 * (Lq >> 5) + (Lq & 7); u.pn = (Lq >> 3) & 3; return true; }
;     __device__ __forceinline__ size_t b_off(const pg8::Unit& u) const { return (size_t)(u.pm >> 3) * 4 * 131072; }
;     ...
;         const bool has_next = S.next(ui + 1, nxt);
;         const char* nA = has_next ? (const char*)g.A + (size_t)nxt.pm * tstepA + (size_t)nxt.pn * APN + kofA : cA; const char* nB = has_next ? (const char*)g.Bt + (size_t)nxt.pn * tstepB + S.b_off(nxt) + kofB : cB;
;     __device__ __forceinline__ void operator()(f32x4 (&acc)[2][2][4][2], const pg8::Unit& u, int ui, int wr, int wc, int fr, int fq) const {
;     ...
;         {   f32x4 swa[2], swv[2];
; #pragma unroll
;             for (int n = 0; n < 2; ++n) { swa[n] = *(const f32x4*)(SW + (size_t)b * NUP + swc + n * 4); swv[n] = *(const f32x4*)(SW + (size_t)b * NUP + swc + 128 + n * 4); }
.Lup_s_1255:
	s_ashr_i32 s27, s26, 31
	s_lshl_b64 s[28:29], s[26:27], 20
	s_add_u32 s28, s2, s28
	s_addc_u32 s29, s33, s29
	s_and_b64 s[30:31], s[6:7], exec
	s_cselect_b32 s27, s29, s35
	s_cselect_b32 s57, s28, s34
	s_ashr_i32 s25, s24, 31
	s_lshl_b64 s[30:31], s[24:25], 20
	s_add_u32 s30, s40, s30
	s_addc_u32 s31, s41, s31
	s_and_b64 s[46:47], s[6:7], exec
	s_cselect_b32 s25, s31, s37
	s_cselect_b32 vcc_lo, s30, s36
	s_add_u32 vcc_hi, s36, 0x10000
	s_addc_u32 s65, s37, 0
	s_mov_b32 s66, -2
	v_mbcnt_lo_u32_b32 v228, -1, 0
	v_mbcnt_hi_u32_b32 v228, -1, v228
	v_ashrrev_i32_e32 v228, 1, v228
	v_and_b32_e32 v228, -8, v228
	s_lshl_b32 s100, s11, 8
	s_or_b32 s100, s100, s83
	v_add_u32_e32 v228, s100, v228
	v_ashrrev_i32_e32 v229, 31, v228
	s_ashr_i32 s100, s10, 4
	s_mul_hi_i32 s101, s100, 0xb000
	s_mul_i32 s100, s100, 0xb000
	s_add_u32 s100, s61, s100
	s_addc_u32 s101, s63, s101
	v_lshl_add_u64 v[228:229], v[228:229], 2, s[100:101]
	global_load_dwordx4 v[212:215], v[228:229], off offset:16
	global_load_dwordx4 v[216:219], v[228:229], off
	global_load_dwordx4 v[220:223], v[228:229], off offset:528
	global_load_dwordx4 v[224:227], v[228:229], off offset:512
	s_cmp_eq_u64 s[12:13], 0
	s_cbranch_scc1 .Lup_nostg
	s_barrier

;     ...
; #pragma unroll
;         for (int a = 0; a < 2; ++a)
; #pragma unroll
;             for (int b = 0; b < 2; ++b)
; #pragma unroll
;                 for (int m = 0; m < 4; ++m)
; #pragma unroll
;                     for (int n = 0; n < 2; ++n) acc[a][b][m][n] = (f32x4){0.f, 0.f, 0.f, 0.f};
;         cur = nxt; cA = nA; cB = nB; ++ui;
;     __device__ __forceinline__ void operator()(f32x4 (&acc)[2][2][4][2], const pg8::Unit& u, int ui, int wr, int wc, int fr, int fq) const {
;     ...
;         {   f32x4 swa[2], swv[2];
; #pragma unroll
;             for (int n = 0; n < 2; ++n) { swa[n] = *(const f32x4*)(SW + (size_t)b * NUP + swc + n * 4); swv[n] = *(const f32x4*)(SW + (size_t)b * NUP + swc + 128 + n * 4); }
.LBB0_1255:
	s_ashr_i32 s27, s26, 31
	s_lshl_b64 s[28:29], s[26:27], 20
	s_add_u32 s28, s2, s28
	s_addc_u32 s29, s33, s29
	s_and_b64 s[30:31], s[6:7], exec
	s_cselect_b32 s27, s29, s35
	s_cselect_b32 s57, s28, s34
	s_ashr_i32 s25, s24, 31
	s_lshl_b64 s[30:31], s[24:25], 20
	s_add_u32 s30, s40, s30
	s_addc_u32 s31, s41, s31
	s_and_b64 s[46:47], s[6:7], exec
	s_cselect_b32 s25, s31, s37
	s_cselect_b32 vcc_lo, s30, s36
	s_add_u32 vcc_hi, s36, 0x10000
	v_mov_b32_e32 v10, 0
	s_addc_u32 s65, s37, 0
	s_mov_b32 s66, -2
	v_mov_b32_e32 v11, v10
	v_mov_b32_e32 v12, v10
	v_mov_b32_e32 v13, v10
	v_mov_b32_e32 v14, v10
	v_mov_b32_e32 v15, v10
	v_mov_b32_e32 v16, v10
	v_mov_b32_e32 v17, v10
	v_mov_b32_e32 v18, v10
	v_mov_b32_e32 v19, v10
	v_mov_b32_e32 v20, v10
	v_mov_b32_e32 v21, v10
	v_mov_b32_e32 v22, v10
	v_mov_b32_e32 v23, v10
	v_mov_b32_e32 v24, v10
	v_mov_b32_e32 v25, v10
	v_mov_b32_e32 v50, v10
	v_mov_b32_e32 v51, v10
	v_mov_b32_e32 v52, v10
	v_mov_b32_e32 v53, v10
	v_mov_b32_e32 v54, v10
	v_mov_b32_e32 v55, v10
	v_mov_b32_e32 v56, v10
	v_mov_b32_e32 v57, v10
	v_mov_b32_e32 v58, v10
	v_mov_b32_e32 v59, v10
	v_mov_b32_e32 v60, v10
	v_mov_b32_e32 v61, v10
	v_mov_b32_e32 v62, v10
	v_mov_b32_e32 v63, v10
	v_mov_b32_e32 v64, v10
	v_mov_b32_e32 v65, v10
	v_mov_b32_e32 v2, v10
	v_mov_b32_e32 v3, v10
	v_mov_b32_e32 v4, v10
	v_mov_b32_e32 v5, v10
	v_mov_b32_e32 v38, v10
	v_mov_b32_e32 v39, v10
	v_mov_b32_e32 v40, v10
	v_mov_b32_e32 v41, v10
	v_mov_b32_e32 v6, v10
	v_mov_b32_e32 v7, v10
	v_mov_b32_e32 v8, v10
	v_mov_b32_e32 v9, v10
	v_mov_b32_e32 v42, v10
	v_mov_b32_e32 v43, v10
	v_mov_b32_e32 v44, v10
	v_mov_b32_e32 v45, v10
	v_mov_b32_e32 v66, v10
	v_mov_b32_e32 v67, v10
	v_mov_b32_e32 v68, v10
	v_mov_b32_e32 v69, v10
	v_mov_b32_e32 v70, v10
	v_mov_b32_e32 v71, v10
	v_mov_b32_e32 v72, v10
	v_mov_b32_e32 v73, v10
	v_mov_b32_e32 v74, v10
	v_mov_b32_e32 v75, v10
	v_mov_b32_e32 v76, v10
	v_mov_b32_e32 v77, v10
	v_mov_b32_e32 v78, v10
	v_mov_b32_e32 v79, v10
	v_mov_b32_e32 v80, v10
	v_mov_b32_e32 v81, v10
	v_mov_b32_e32 v82, v10
	v_mov_b32_e32 v83, v10
	v_mov_b32_e32 v84, v10
	v_mov_b32_e32 v85, v10
	v_mov_b32_e32 v86, v10
	v_mov_b32_e32 v87, v10
	v_mov_b32_e32 v88, v10
	v_mov_b32_e32 v89, v10
	v_mov_b32_e32 v90, v10
	v_mov_b32_e32 v91, v10
	v_mov_b32_e32 v92, v10
	v_mov_b32_e32 v93, v10
	v_mov_b32_e32 v94, v10
	v_mov_b32_e32 v95, v10
	v_mov_b32_e32 v96, v10
	v_mov_b32_e32 v97, v10
	v_mov_b32_e32 v34, v10
	v_mov_b32_e32 v35, v10
	v_mov_b32_e32 v36, v10
	v_mov_b32_e32 v37, v10
	v_mov_b32_e32 v26, v10
	v_mov_b32_e32 v27, v10
	v_mov_b32_e32 v28, v10
	v_mov_b32_e32 v29, v10
	v_mov_b32_e32 v46, v10
	v_mov_b32_e32 v47, v10
	v_mov_b32_e32 v48, v10
	v_mov_b32_e32 v49, v10
	v_mov_b32_e32 v30, v10
	v_mov_b32_e32 v31, v10
	v_mov_b32_e32 v32, v10
	v_mov_b32_e32 v33, v10
	v_mov_b32_e32 v98, v10
	v_mov_b32_e32 v99, v10
	v_mov_b32_e32 v100, v10
	v_mov_b32_e32 v101, v10
	v_mov_b32_e32 v102, v10
	v_mov_b32_e32 v103, v10
	v_mov_b32_e32 v104, v10
	v_mov_b32_e32 v105, v10
	v_mov_b32_e32 v106, v10
	v_mov_b32_e32 v107, v10
	v_mov_b32_e32 v108, v10
	v_mov_b32_e32 v109, v10
	v_mov_b32_e32 v110, v10
	v_mov_b32_e32 v111, v10
	v_mov_b32_e32 v112, v10
	v_mov_b32_e32 v113, v10
	v_mov_b32_e32 v114, v10
	v_mov_b32_e32 v115, v10
	v_mov_b32_e32 v116, v10
	v_mov_b32_e32 v117, v10
	v_mov_b32_e32 v118, v10
	v_mov_b32_e32 v119, v10
	v_mov_b32_e32 v120, v10
	v_mov_b32_e32 v121, v10
	v_mov_b32_e32 v122, v10
	v_mov_b32_e32 v123, v10
	v_mov_b32_e32 v124, v10
	v_mov_b32_e32 v125, v10
	v_mov_b32_e32 v126, v10
	v_mov_b32_e32 v127, v10
	v_mov_b32_e32 v128, v10
	v_mov_b32_e32 v129, v10
	v_mbcnt_lo_u32_b32 v228, -1, 0
	v_mbcnt_hi_u32_b32 v228, -1, v228
	v_ashrrev_i32_e32 v228, 1, v228
	v_and_b32_e32 v228, -8, v228
	s_lshl_b32 s100, s11, 8
	s_or_b32 s100, s100, s83
	v_add_u32_e32 v228, s100, v228
	v_ashrrev_i32_e32 v229, 31, v228
	s_ashr_i32 s100, s10, 4
	s_mul_hi_i32 s101, s100, 0xb000
	s_mul_i32 s100, s100, 0xb000
	s_add_u32 s100, s61, s100
	s_addc_u32 s101, s63, s101
	v_lshl_add_u64 v[228:229], v[228:229], 2, s[100:101]
	global_load_dwordx4 v[212:215], v[228:229], off offset:16
	global_load_dwordx4 v[216:219], v[228:229], off
	global_load_dwordx4 v[220:223], v[228:229], off offset:528
	global_load_dwordx4 v[224:227], v[228:229], off offset:512

; __device__ __forceinline__ void store_wt(void* p, const u32x4 v) { asm volatile("global_store_dwordx4 %0, %1, off sc1\n\ts_nop 2" :: "v"(p), "v"(v) : "memory"); }
;     __device__ __forceinline__ void operator()(f32x4 (&acc)[2][2][4][2], const pg8::Unit& u, int ui, int wr, int wc, int fr, int fq) const {
;         const int b = u.pm >> 4, lrow = wr * 128 + fr * 8, jc = u.pn * 128 + wc * 32 + fq * 8, swc = u.pn * 256 + wc * 32 + fq * 8;
;         {   f32x4 swa[2], swv[2];
; #pragma unroll
;             for (int n = 0; n < 2; ++n) { swa[n] = *(const f32x4*)(SW + (size_t)b * NUP + swc + n * 4); swv[n] = *(const f32x4*)(SW + (size_t)b * NUP + swc + 128 + n * 4); }
; #pragma unroll
;             for (int ai = 0; ai < 2; ++ai)
; #pragma unroll
;                 for (int m = 0; m < 4; ++m) { const float r = RSTD[ui * 256 + lrow + 4 * ai + m];
; #pragma unroll
;                     for (int n = 0; n < 2; ++n) { acc[ai][0][m][n] = acc[ai][0][m][n] * r + swa[n]; acc[ai][1][m][n] = acc[ai][1][m][n] * r + swv[n]; } }
;         }
;         {   const int kb = u.pm * 2 + wr;
;             if (fr == 0) { float* pa = HA + ((size_t)kb * 4) * DFF + jc; float* pv = HV + ((size_t)kb * 2) * DFF + jc;
;                 *(f32x4*)pa = acc[0][0][0][0]; *(f32x4*)(pa + 4) = acc[0][0][0][1]; *(f32x4*)(pa + DFF) = acc[0][0][1][0]; *(f32x4*)(pa + DFF + 4) = acc[0][0][1][1];
;                 *(f32x4*)pv = acc[0][1][0][0]; *(f32x4*)(pv + 4) = acc[0][1][0][1]; *(f32x4*)(pv + DFF) = acc[0][1][1][0]; *(f32x4*)(pv + DFF + 4) = acc[0][1][1][1]; }
;             if (fr == 15) { float* pa = HA + ((size_t)kb * 4 + 2) * DFF + jc;
;                 store_wt(pa, __builtin_bit_cast(u32x4, acc[1][0][2][0])); store_wt(pa + 4, __builtin_bit_cast(u32x4, acc[1][0][2][1])); store_wt(pa + DFF, __builtin_bit_cast(u32x4, acc[1][0][3][0])); store_wt(pa + DFF + 4, __builtin_bit_cast(u32x4, acc[1][0][3][1])); } }
.LBB0_1259:
	v_mbcnt_lo_u32_b32 v130, -1, 0
	v_mbcnt_hi_u32_b32 v130, -1, v130
	s_lshl_b32 s27, s11, 8
	v_and_b32_e32 v172, 15, v130
	v_ashrrev_i32_e32 v130, 1, v130
	s_ashr_i32 s25, s10, 4
	v_and_b32_e32 v132, -8, v130
	s_or_b32 s27, s27, s83
	v_add_u32_e32 v130, s27, v132
	s_mul_hi_i32 s27, s25, 0xb000
	s_mul_i32 s25, s25, 0xb000
	s_add_u32 s34, s61, s25
	s_addc_u32 s35, s63, s27
	v_ashrrev_i32_e32 v131, 31, v130
	v_lshl_add_u64 v[130:131], v[130:131], 2, s[34:35]
	v_mov_b32_e32 v142, v212
	v_mov_b32_e32 v143, v213
	v_mov_b32_e32 v144, v214
	v_mov_b32_e32 v145, v215
	v_mov_b32_e32 v150, v216
	v_mov_b32_e32 v151, v217
	v_mov_b32_e32 v152, v218
	v_mov_b32_e32 v153, v219
	v_mov_b32_e32 v134, v220
	v_mov_b32_e32 v135, v221
	v_mov_b32_e32 v136, v222
	v_mov_b32_e32 v137, v223
	v_mov_b32_e32 v138, v224
	v_mov_b32_e32 v139, v225
	v_mov_b32_e32 v140, v226
	v_mov_b32_e32 v141, v227
	s_lshl_b32 s25, s92, 10
	v_lshl_or_b32 v0, v172, 3, s91
	s_add_i32 s25, s25, 0
	v_lshl_add_u32 v130, v0, 2, s25
	v_add_u32_e32 v130, 0x20400, v130
	ds_read_b128 v[154:157], v130
	ds_read_b128 v[146:149], v130 offset:16
	s_lshl_b32 s11, s11, 7
	s_or_b32 s11, s11, s83
	v_add_u32_e32 v170, s11, v132
	s_lshl_b32 s11, s10, 1
	s_waitcnt lgkmcnt(0)
	v_mov_b32_e32 v130, v149
	s_add_i32 s11, s11, s55
	v_cmp_lt_i32_e32 vcc, 14, v172
	v_ashrrev_i32_e32 v171, 31, v170
	s_waitcnt vmcnt(8)
	v_pk_fma_f32 v[8:9], v[8:9], v[148:149], v[144:145] op_sel_hi:[1,0,1]
	v_pk_fma_f32 v[44:45], v[44:45], v[148:149], v[152:153] op_sel_hi:[1,0,1]
	v_pk_fma_f32 v[42:43], v[42:43], v[148:149], v[150:151] op_sel_hi:[1,0,1]
	v_pk_fma_f32 v[6:7], v[6:7], v[148:149], v[142:143] op_sel_hi:[1,0,1]
	v_pk_fma_f32 v[40:41], v[40:41], v[130:131], v[152:153] op_sel_hi:[1,0,1]
	v_pk_fma_f32 v[38:39], v[38:39], v[130:131], v[150:151] op_sel_hi:[1,0,1]
	v_pk_fma_f32 v[4:5], v[4:5], v[130:131], v[144:145] op_sel_hi:[1,0,1]
	v_pk_fma_f32 v[2:3], v[2:3], v[130:131], v[142:143] op_sel_hi:[1,0,1]
	s_and_saveexec_b64 s[34:35], vcc
	s_xor_b64 s[34:35], exec, s[34:35]
	s_cbranch_execz .LBB0_1261
	s_mul_i32 s27, s11, 0x16000
	s_mul_hi_i32 s25, s11, 0x16000
	s_add_u32 s36, s70, s27
	s_addc_u32 s37, s71, s25
	v_lshl_add_u64 v[130:131], v[170:171], 2, s[36:37]
	s_mov_b64 s[36:37], 0xb000
	v_lshl_add_u64 v[132:133], v[130:131], 0, s[36:37]
	global_store_dwordx4 v[132:133], v[42:45], off sc1
	s_nop 2
	s_mov_b64 s[36:37], 0xb010
	v_lshl_add_u64 v[132:133], v[130:131], 0, s[36:37]
	global_store_dwordx4 v[132:133], v[6:9], off sc1
	s_nop 2
	s_mov_b64 s[36:37], 0x10800
	v_lshl_add_u64 v[132:133], v[130:131], 0, s[36:37]
	global_store_dwordx4 v[132:133], v[38:41], off sc1
	s_nop 2
	s_mov_b64 s[36:37], 0x10810
	v_lshl_add_u64 v[130:131], v[130:131], 0, s[36:37]
	global_store_dwordx4 v[130:131], v[2:5], off sc1
	s_nop 2
